# baseline (speedup 1.0000x reference)
; template <bool MLA>
; __device__ __forceinline__ float attn_scores(f32x16& sa, float c1, float slope2, int qpos, int q0w, int kpos0, int h5, bool maskit) {
;     float mx = -INFINITY;
;     if constexpr (MLA) {
; #pragma unroll
;         for (int r = 0; r < 16; ++r) {
;             float v = sa[r] * c1;
;             if (maskit && (kpos0 + 8 * (r >> 2) + (r & 3) + 4 * h5 >= L)) v = -INFINITY;
;             sa[r] = v;
;             mx = fmaxf(mx, v);
;         }
;     } else {
;         const float dq = (float)(qpos - kpos0 - 4 * h5);
;         const int rel = q0w - kpos0;
;         if (rel > 31 || rel < -31) {
;             const float sgn = rel > 0 ? 1.0f : -1.0f;
;             const float A = -sgn * slope2 * dq;
;             const float ss = sgn * slope2;
; #pragma unroll
; template <bool MLA>
; __device__ __forceinline__ void attn_item(unsigned char* smem, const Params& p, int b, int hh, int qt) {
;     ...
;     for (int kt = 0; kt < NKT; ++kt) {
;         const int k0 = kt * 64;
;         const unsigned char* Kc = S0 + stage * STGB;
;         const unsigned char* Vc = Kc + KBYTES;
;         if (kt + 2 < NKT) { const int st2 = stage >= 1 ? stage - 1 : 2; ATTN_DMA(st2); }
;         bf16x8 ka[4], kb[4], kc[4], vf[8];
; #pragma unroll
;         for (int i = 0; i < 4; ++i) ka[i] = KRD(0, i);
;         SB_();
; #pragma unroll
;         for (int hf = 0; hf < 2; ++hf) {
;             if (hf == 1 && kt == NKT - 1) break;
;             f32x16 sa;
; #pragma unroll
;             for (int r = 0; r < 16; ++r) sa[r] = 0.f;
;             if constexpr (MLA) {
;                 __builtin_amdgcn_s_setprio(1);
; #pragma unroll
;                 for (int i = 0; i < 4; ++i) {
;                     sa = __builtin_amdgcn_mfma_f32_32x32x16_bf16(ka[i], qf[i], sa, 0, 0, 0);
;                     kb[i] = KRD(hf, 4 + i);
;                 }
;                 SB_();
; #pragma unroll
;                 for (int i = 0; i < 4; ++i) {
;                     sa = __builtin_amdgcn_mfma_f32_32x32x16_bf16(kb[i], qf[4 + i], sa, 0, 0, 0);
;                     kc[i] = KRD(hf, 8 + i);
;                 }
;                 SB_();
; #pragma unroll
;                 for (int d = 0; d < 2; ++d) { vf[2 * d] = VRD(hf, d, 0); vf[2 * d + 1] = VRD(hf, d, 1); }
; #pragma unroll
;                 for (int i = 0; i < 4; ++i) sa = __builtin_amdgcn_mfma_f32_32x32x16_bf16(kc[i], qf[8 + i], sa, 0, 0, 0);
.LBB0_866:
	v_sub_f32_e32 v74, v212, v198
	v_sub_f32_e32 v75, v211, v198
	v_sub_f32_e32 v76, v210, v198
	v_sub_f32_e32 v77, v208, v198
	v_sub_f32_e32 v78, v207, v198
	v_sub_f32_e32 v79, v206, v198
	v_sub_f32_e32 v80, v205, v198
	v_sub_f32_e32 v81, v204, v198
	v_sub_f32_e32 v73, v73, v198
	v_sub_f32_e32 v72, v72, v198
	v_sub_f32_e32 v71, v71, v198
	v_sub_f32_e32 v70, v70, v198
	v_sub_f32_e32 v69, v69, v198
	v_sub_f32_e32 v68, v68, v198
	v_sub_f32_e32 v67, v67, v198
	v_sub_f32_e32 v66, v66, v198
	v_exp_f32_e32 v74, v74
	v_exp_f32_e32 v75, v75
	v_exp_f32_e32 v76, v76
	v_exp_f32_e32 v77, v77
	v_exp_f32_e32 v78, v78
	v_exp_f32_e32 v79, v79
	v_exp_f32_e32 v80, v80
	v_exp_f32_e32 v81, v81
	v_exp_f32_e32 v73, v73
	v_exp_f32_e32 v72, v72
	v_exp_f32_e32 v71, v71
	v_exp_f32_e32 v70, v70
	v_exp_f32_e32 v69, v69
	v_exp_f32_e32 v68, v68
	v_exp_f32_e32 v204, v67
	v_exp_f32_e32 v205, v66
	v_add_f32_e32 v66, v201, v74
	v_add_f32_e32 v66, v75, v66
	v_add_f32_e32 v66, v76, v66
	v_add_f32_e32 v66, v77, v66
	v_add_f32_e32 v66, v78, v66
	v_add_f32_e32 v66, v79, v66
	v_add_f32_e32 v66, v80, v66
	v_add_f32_e32 v66, v81, v66
	v_add_f32_e32 v66, v73, v66
	v_add_f32_e32 v66, v72, v66
	v_add_f32_e32 v66, v71, v66
	v_add_f32_e32 v66, v70, v66
	v_add_f32_e32 v66, v69, v66
	v_add_f32_e32 v66, v68, v66
	v_add_f32_e32 v66, v204, v66
	v_add_f32_e32 v201, v205, v66
	v_cvt_pk_bf16_f32 v66, v73, v72
	v_cvt_pk_bf16_f32 v67, v71, v70
	v_cvt_pk_bf16_f32 v68, v69, v68
	v_cvt_pk_bf16_f32 v69, v204, v205
	v_cvt_pk_bf16_f32 v70, v74, v75
	v_cvt_pk_bf16_f32 v71, v76, v77
	v_cvt_pk_bf16_f32 v72, v78, v79
	v_cvt_pk_bf16_f32 v73, v80, v81
	ds_read_b128 v[74:77], v202 offset:36864
	ds_read_b128 v[78:81], v203 offset:36864
	ds_read_b128 v[204:207], v202 offset:32768
	ds_read_b128 v[208:211], v203 offset:32768
	s_setprio 1
	s_waitcnt lgkmcnt(4)
	v_mfma_f32_32x32x16_bf16 v[50:65], v[138:141], v[70:73], v[50:65]
	v_mfma_f32_32x32x16_bf16 v[34:49], v[130:133], v[70:73], v[34:49]
	s_waitcnt lgkmcnt(0)
	v_mfma_f32_32x32x16_bf16 v[18:33], v[208:211], v[70:73], v[18:33]
	v_mfma_f32_32x32x16_bf16 v[2:17], v[78:81], v[70:73], v[2:17]
	v_mfma_f32_32x32x16_bf16 v[50:65], v[142:145], v[66:69], v[50:65]
	v_mfma_f32_32x32x16_bf16 v[34:49], v[134:137], v[66:69], v[34:49]
	v_mfma_f32_32x32x16_bf16 v[18:33], v[204:207], v[66:69], v[18:33]
	v_mfma_f32_32x32x16_bf16 v[2:17], v[74:77], v[66:69], v[2:17]
	s_setprio 0
	s_add_i32 s3, s2, 1
	s_cmp_lg_u32 s2, 2
	s_waitcnt vmcnt(5)
	s_cselect_b32 s2, s3, 0
	s_add_u32 s0, s0, 0x80
	s_addc_u32 s1, s1, 0
	v_lshl_add_u64 v[158:159], v[158:159], 0, v[154:155]
	v_lshl_add_u64 v[160:161], v[160:161], 0, v[152:153]
	s_cmpk_eq_i32 s0, 0x1f80
	v_lshl_add_u64 v[162:163], v[162:163], 0, v[0:1]
	s_barrier
	s_cbranch_scc1 .LBB0_871
.LBB0_867:
	s_mul_i32 s3, s2, 0xa000
	s_add_i32 s6, s3, 0xffff6000
	s_cmp_gt_i32 s2, 0
	s_cselect_b32 s6, s6, 0x14000
	v_add_u32_e32 v70, s6, v199
	v_add_u32_e32 v71, 0x2000, v70
	v_readfirstlane_b32 s6, v70
	s_mov_b32 m0, s6
	v_readfirstlane_b32 s6, v71
	v_add_u32_e32 v71, 0x4000, v70
	global_load_lds_dwordx4 v[162:163], off
	s_mov_b32 m0, s6
	v_readfirstlane_b32 s6, v71
	v_add_u32_e32 v71, 0x6000, v70
	global_load_lds_dwordx4 v[160:161], off
	s_mov_b32 m0, s6
	v_readfirstlane_b32 s6, v71
	v_lshl_add_u64 v[68:69], v[156:157], 0, s[0:1]
	global_load_lds_dwordx4 v[158:159], off
	s_mov_b32 m0, s6
	v_lshl_add_u64 v[66:67], v[164:165], 0, s[0:1]
	global_load_lds_dwordx4 v[68:69], off
	v_add_u32_e32 v68, 0x8000, v70
	v_add_u32_e32 v70, s3, v200
	v_readfirstlane_b32 s6, v68
	s_mov_b32 m0, s6
	v_add_u32_e32 v203, v70, v192
	global_load_lds_dwordx4 v[66:67], off
	v_add_u32_e32 v205, v70, v196
	v_add_u32_e32 v204, v70, v193
	ds_read_b128 v[66:69], v203
	ds_read_b128 v[130:133], v204
	v_add_u32_e32 v206, v70, v197
	ds_read_b128 v[134:137], v205
	ds_read_b128 v[138:141], v206
	v_or_b32_e32 v202, s3, v194
	s_setprio 1
	s_waitcnt lgkmcnt(0)
	v_mfma_f32_32x32x16_bf16 v[66:81], v[66:69], v[110:113], 0
	ds_read_b128 v[142:145], v203 offset:128
	v_mfma_f32_32x32x16_bf16 v[66:81], v[130:133], v[106:109], v[66:81]
	ds_read_b128 v[130:133], v204 offset:128
	v_mfma_f32_32x32x16_bf16 v[66:81], v[134:137], v[102:105], v[66:81]
	ds_read_b128 v[134:137], v205 offset:128
	v_mfma_f32_32x32x16_bf16 v[66:81], v[138:141], v[98:101], v[66:81]
	ds_read_b128 v[138:141], v206 offset:128
	ds_read_b128 v[208:211], v203 offset:256
	ds_read_b128 v[212:215], v204 offset:256
	ds_read_b128 v[222:225], v205 offset:256
	ds_read_b128 v[226:229], v206 offset:256
	s_waitcnt lgkmcnt(0)
	v_mfma_f32_32x32x16_bf16 v[66:81], v[142:145], v[94:97], v[66:81]
	v_add_u32_e32 v207, v202, v193
	v_mfma_f32_32x32x16_bf16 v[66:81], v[130:133], v[90:93], v[66:81]
	v_mfma_f32_32x32x16_bf16 v[66:81], v[134:137], v[86:89], v[66:81]
	v_mfma_f32_32x32x16_bf16 v[66:81], v[138:141], v[82:85], v[66:81]
	v_mfma_f32_32x32x16_bf16 v[66:81], v[208:211], v[118:121], v[66:81]
	v_add_u32_e32 v208, v202, v192
	ds_read_b128 v[138:141], v208 offset:24576
	ds_read_b128 v[130:133], v208 offset:28672
	ds_read_b128 v[142:145], v207 offset:24576
	ds_read_b128 v[134:137], v207 offset:28672
	v_mfma_f32_32x32x16_bf16 v[66:81], v[212:215], v[126:129], v[66:81]
	v_mfma_f32_32x32x16_bf16 v[66:81], v[222:225], v[114:117], v[66:81]
	v_mfma_f32_32x32x16_bf16 v[66:81], v[226:229], v[122:125], v[66:81]
	s_setprio 0
	s_nop 10
	v_mul_f32_e32 v217, 0x3dd53b94, v66
	v_mul_f32_e32 v216, 0x3dd53b94, v67
	s_mov_b32 s3, 0xff800000
	v_mul_f32_e32 v215, 0x3dd53b94, v68
	v_mul_f32_e32 v214, 0x3dd53b94, v69
	v_mul_f32_e32 v210, 0x3dd53b94, v73
	v_mul_f32_e32 v73, 0x3dd53b94, v74
	v_max3_f32 v74, v217, s3, v216
	v_mul_f32_e32 v213, 0x3dd53b94, v70
	v_mul_f32_e32 v212, 0x3dd53b94, v71
	v_max3_f32 v74, v74, v215, v214
	v_mul_f32_e32 v211, 0x3dd53b94, v72
	v_max3_f32 v74, v74, v213, v212
	v_mul_f32_e32 v72, 0x3dd53b94, v75
	v_max3_f32 v74, v74, v211, v210
	v_mul_f32_e32 v71, 0x3dd53b94, v76
	v_mul_f32_e32 v70, 0x3dd53b94, v77
	v_max3_f32 v74, v74, v73, v72
	v_mul_f32_e32 v69, 0x3dd53b94, v78
	v_mul_f32_e32 v68, 0x3dd53b94, v79
	v_max3_f32 v74, v74, v71, v70
	v_mul_f32_e32 v67, 0x3dd53b94, v80
	v_mul_f32_e32 v66, 0x3dd53b94, v81
	v_max3_f32 v74, v74, v69, v68
	v_max3_f32 v74, v74, v67, v66
	v_mov_b32_e32 v75, v74
	v_add_f32_e32 v209, 0x41000000, v198
	s_nop 0
	v_permlane32_swap_b32_e32 v74, v75
	v_max_f32_e32 v74, v74, v75
	v_cmp_le_f32_e32 vcc, v74, v209
	s_cmp_eq_u64 vcc, exec
	s_cbranch_scc1 .LBB0_869
; __device__ __forceinline__ void attn_exp(f32x16& sa, float mx, float& m_run, float& lsum, f32x16 (&o)[4], bf16x8& pb0, bf16x8& pb1) {
;     if (!__all(mx <= m_run + ATT_THR)) {
;         const float m_new = fmaxf(m_run, mx);
;         const float alpha = __builtin_amdgcn_exp2f(m_run - m_new);
;         m_run = m_new;
;         lsum *= alpha;
; #pragma unroll
;         for (int d = 0; d < 4; ++d)
; #pragma unroll
;             for (int r = 0; r < 16; ++r) o[d][r] *= alpha;
;     }
;     float pv[16];
; #pragma unroll
;     for (int r = 0; r < 16; ++r) { pv[r] = __builtin_amdgcn_exp2f(sa[r] - m_run); lsum += pv[r]; }
;     u32x4 t0 = {pack2(pv[0], pv[1]), pack2(pv[2], pv[3]), pack2(pv[4], pv[5]), pack2(pv[6], pv[7])};
;     u32x4 t1 = {pack2(pv[8], pv[9]), pack2(pv[10], pv[11]), pack2(pv[12], pv[13]), pack2(pv[14], pv[15])};
;     pb0 = __builtin_bit_cast(bf16x8, t0);
;     pb1 = __builtin_bit_cast(bf16x8, t1);
; }
; template <bool MLA>
; __device__ __forceinline__ void attn_item(unsigned char* smem, const Params& p, int b, int hh, int qt) {
;     ...
;             if constexpr (MLA) {
; #pragma unroll
;                 for (int d = 2; d < 4; ++d) { vf[2 * d] = VRD(hf, d, 0); vf[2 * d + 1] = VRD(hf, d, 1); }
;             }
;             if (hf == 0 && kt != NKT - 1) {
; #pragma unroll
;                 for (int i = 0; i < 4; ++i) ka[i] = KRD(1, i);
;             }
;             __builtin_amdgcn_s_setprio(1);
; #pragma unroll
;             for (int d = 0; d < 4; ++d) {
;                 o[d] = __builtin_amdgcn_mfma_f32_32x32x16_bf16(vf[2 * d], pb0, o[d], 0, 0, 0);
;                 o[d] = __builtin_amdgcn_mfma_f32_32x32x16_bf16(vf[2 * d + 1], pb1, o[d], 0, 0, 0);
	v_max_f32_e32 v74, v74, v74
	v_max_f32_e32 v75, v198, v198
	v_max_f32_e32 v75, v75, v74
	v_sub_f32_e32 v74, v198, v75
	v_exp_f32_e32 v74, v74
	v_add_f32_e32 v209, 0x41000000, v75
	v_mov_b32_e32 v198, v75
	v_mul_f32_e32 v201, v201, v74
	v_pk_mul_f32 v[64:65], v[64:65], v[74:75] op_sel_hi:[1,0]
	v_pk_mul_f32 v[62:63], v[62:63], v[74:75] op_sel_hi:[1,0]
	v_pk_mul_f32 v[60:61], v[60:61], v[74:75] op_sel_hi:[1,0]
	v_pk_mul_f32 v[58:59], v[58:59], v[74:75] op_sel_hi:[1,0]
	v_pk_mul_f32 v[56:57], v[56:57], v[74:75] op_sel_hi:[1,0]
	v_pk_mul_f32 v[54:55], v[54:55], v[74:75] op_sel_hi:[1,0]
	v_pk_mul_f32 v[52:53], v[52:53], v[74:75] op_sel_hi:[1,0]
	v_pk_mul_f32 v[50:51], v[50:51], v[74:75] op_sel_hi:[1,0]
	v_pk_mul_f32 v[48:49], v[48:49], v[74:75] op_sel_hi:[1,0]
	v_pk_mul_f32 v[46:47], v[46:47], v[74:75] op_sel_hi:[1,0]
	v_pk_mul_f32 v[44:45], v[44:45], v[74:75] op_sel_hi:[1,0]
	v_pk_mul_f32 v[42:43], v[42:43], v[74:75] op_sel_hi:[1,0]
	v_pk_mul_f32 v[40:41], v[40:41], v[74:75] op_sel_hi:[1,0]
	v_pk_mul_f32 v[38:39], v[38:39], v[74:75] op_sel_hi:[1,0]
	v_pk_mul_f32 v[36:37], v[36:37], v[74:75] op_sel_hi:[1,0]
	v_pk_mul_f32 v[34:35], v[34:35], v[74:75] op_sel_hi:[1,0]
	v_pk_mul_f32 v[32:33], v[32:33], v[74:75] op_sel_hi:[1,0]
	v_pk_mul_f32 v[30:31], v[30:31], v[74:75] op_sel_hi:[1,0]
	v_pk_mul_f32 v[28:29], v[28:29], v[74:75] op_sel_hi:[1,0]
	v_pk_mul_f32 v[26:27], v[26:27], v[74:75] op_sel_hi:[1,0]
	v_pk_mul_f32 v[24:25], v[24:25], v[74:75] op_sel_hi:[1,0]
	v_pk_mul_f32 v[22:23], v[22:23], v[74:75] op_sel_hi:[1,0]
	v_pk_mul_f32 v[20:21], v[20:21], v[74:75] op_sel_hi:[1,0]
	v_pk_mul_f32 v[18:19], v[18:19], v[74:75] op_sel_hi:[1,0]
	v_pk_mul_f32 v[16:17], v[16:17], v[74:75] op_sel_hi:[1,0]
	v_pk_mul_f32 v[14:15], v[14:15], v[74:75] op_sel_hi:[1,0]
	v_pk_mul_f32 v[12:13], v[12:13], v[74:75] op_sel_hi:[1,0]
	v_pk_mul_f32 v[10:11], v[10:11], v[74:75] op_sel_hi:[1,0]
	v_pk_mul_f32 v[8:9], v[8:9], v[74:75] op_sel_hi:[1,0]
	v_pk_mul_f32 v[6:7], v[6:7], v[74:75] op_sel_hi:[1,0]
	v_pk_mul_f32 v[4:5], v[4:5], v[74:75] op_sel_hi:[1,0]
	v_pk_mul_f32 v[2:3], v[2:3], v[74:75] op_sel_hi:[1,0]
.LBB0_869:
	v_sub_f32_e32 v74, v217, v198
	v_exp_f32_e32 v222, v74
	v_sub_f32_e32 v74, v216, v198
	v_exp_f32_e32 v223, v74
	v_sub_f32_e32 v74, v215, v198
	v_exp_f32_e32 v224, v74
	v_sub_f32_e32 v74, v214, v198
	v_exp_f32_e32 v225, v74
	v_sub_f32_e32 v74, v213, v198
	v_exp_f32_e32 v226, v74
	v_sub_f32_e32 v74, v212, v198
	v_exp_f32_e32 v227, v74
	v_sub_f32_e32 v74, v211, v198
	v_exp_f32_e32 v228, v74
	v_sub_f32_e32 v74, v210, v198
	v_sub_f32_e32 v73, v73, v198
	v_sub_f32_e32 v72, v72, v198
	v_sub_f32_e32 v71, v71, v198
	v_sub_f32_e32 v70, v70, v198
	v_sub_f32_e32 v69, v69, v198
	v_sub_f32_e32 v68, v68, v198
	v_sub_f32_e32 v67, v67, v198
	v_sub_f32_e32 v66, v66, v198
	v_exp_f32_e32 v229, v74
	v_exp_f32_e32 v230, v73
	v_exp_f32_e32 v231, v72
	v_exp_f32_e32 v232, v71
	v_exp_f32_e32 v233, v70
	v_exp_f32_e32 v234, v69
	v_exp_f32_e32 v235, v68
	v_exp_f32_e32 v236, v67
	v_exp_f32_e32 v237, v66
	v_cvt_pk_bf16_f32 v66, v222, v223
	v_cvt_pk_bf16_f32 v67, v224, v225
	v_cvt_pk_bf16_f32 v68, v226, v227
	v_cvt_pk_bf16_f32 v69, v228, v229
	v_cvt_pk_bf16_f32 v70, v230, v231
	v_cvt_pk_bf16_f32 v71, v232, v233
	v_cvt_pk_bf16_f32 v72, v234, v235
	v_cvt_pk_bf16_f32 v73, v236, v237
	v_add_f32_e32 v201, v201, v222
	v_add_f32_e32 v201, v223, v201
	v_add_f32_e32 v201, v224, v201
	v_add_f32_e32 v201, v225, v201
	v_add_f32_e32 v201, v226, v201
	v_add_f32_e32 v201, v227, v201
	v_add_f32_e32 v201, v228, v201
	v_add_f32_e32 v201, v229, v201
	v_add_f32_e32 v201, v230, v201
	v_add_f32_e32 v201, v231, v201
	v_add_f32_e32 v201, v232, v201
	v_add_f32_e32 v201, v233, v201
	v_add_f32_e32 v201, v234, v201
	v_add_f32_e32 v201, v235, v201
	v_add_f32_e32 v201, v236, v201
	ds_read_b128 v[74:77], v208 offset:32768
	ds_read_b128 v[78:81], v207 offset:32768
	ds_read_b128 v[210:213], v208 offset:36864
	ds_read_b128 v[214:217], v207 offset:36864
	v_add_f32_e32 v201, v237, v201
	ds_read_b128 v[222:225], v203 offset:12288
	ds_read_b128 v[226:229], v204 offset:12288
	ds_read_b128 v[230:233], v205 offset:12288
	ds_read_b128 v[234:237], v206 offset:12288
	s_setprio 1
	s_waitcnt lgkmcnt(8)
	v_mfma_f32_32x32x16_bf16 v[50:65], v[138:141], v[66:69], v[50:65]
	v_mfma_f32_32x32x16_bf16 v[34:49], v[130:133], v[66:69], v[34:49]
	s_waitcnt lgkmcnt(0)
; #define SB_() __builtin_amdgcn_sched_barrier(0)
; template <bool MLA>
; __device__ __forceinline__ float attn_scores(f32x16& sa, float c1, float slope2, int qpos, int q0w, int kpos0, int h5, bool maskit) {
;     float mx = -INFINITY;
;     if constexpr (MLA) {
; #pragma unroll
;         for (int r = 0; r < 16; ++r) {
;             float v = sa[r] * c1;
;             if (maskit && (kpos0 + 8 * (r >> 2) + (r & 3) + 4 * h5 >= L)) v = -INFINITY;
;             sa[r] = v;
;             mx = fmaxf(mx, v);
;         }
;     } else {
;         const float dq = (float)(qpos - kpos0 - 4 * h5);
;         const int rel = q0w - kpos0;
;         if (rel > 31 || rel < -31) {
;             const float sgn = rel > 0 ? 1.0f : -1.0f;
;             const float A = -sgn * slope2 * dq;
;             const float ss = sgn * slope2;
; #pragma unroll
;             for (int r = 0; r < 16; ++r) {
;                 const float ko = (float)(8 * (r >> 2) + (r & 3));
;                 float v = fmaf(sa[r], c1, fmaf(ss, ko, A));
;                 if (maskit && (kpos0 + 8 * (r >> 2) + (r & 3) + 4 * h5 >= L)) v = -INFINITY;
;                 sa[r] = v;
;                 mx = fmaxf(mx, v);
;             }
;         } else {
; #pragma unroll
;             for (int r = 0; r < 16; ++r) {
;                 const int ko = 8 * (r >> 2) + (r & 3);
;                 float v = sa[r] * c1 - slope2 * fabsf(dq - (float)ko);
; template <bool MLA>
; __device__ __forceinline__ void attn_item(unsigned char* smem, const Params& p, int b, int hh, int qt) {
;     ...
;             if constexpr (MLA) {
;                 __builtin_amdgcn_s_setprio(1);
; #pragma unroll
;                 for (int i = 0; i < 4; ++i) {
;                     sa = __builtin_amdgcn_mfma_f32_32x32x16_bf16(ka[i], qf[i], sa, 0, 0, 0);
;                     kb[i] = KRD(hf, 4 + i);
;                 }
;                 SB_();
; #pragma unroll
;                 for (int i = 0; i < 4; ++i) {
;                     sa = __builtin_amdgcn_mfma_f32_32x32x16_bf16(kb[i], qf[4 + i], sa, 0, 0, 0);
;                     kc[i] = KRD(hf, 8 + i);
;                 }
;                 SB_();
; #pragma unroll
;                 for (int d = 0; d < 2; ++d) { vf[2 * d] = VRD(hf, d, 0); vf[2 * d + 1] = VRD(hf, d, 1); }
; #pragma unroll
;                 for (int i = 0; i < 4; ++i) sa = __builtin_amdgcn_mfma_f32_32x32x16_bf16(kc[i], qf[8 + i], sa, 0, 0, 0);
	v_mfma_f32_32x32x16_bf16 v[18:33], v[74:77], v[66:69], v[18:33]
	v_mfma_f32_32x32x16_bf16 v[2:17], v[210:213], v[66:69], v[2:17]
	v_mfma_f32_32x32x16_bf16 v[50:65], v[142:145], v[70:73], v[50:65]
	v_mfma_f32_32x32x16_bf16 v[34:49], v[134:137], v[70:73], v[34:49]
	v_mfma_f32_32x32x16_bf16 v[18:33], v[78:81], v[70:73], v[18:33]
	v_mfma_f32_32x32x16_bf16 v[2:17], v[214:217], v[70:73], v[2:17]
	s_setprio 0
	s_setprio 1
	v_mfma_f32_32x32x16_bf16 v[66:81], v[222:225], v[110:113], 0
	ds_read_b128 v[130:133], v203 offset:12416
	ds_read_b128 v[134:137], v204 offset:12416
	ds_read_b128 v[138:141], v205 offset:12416
	ds_read_b128 v[142:145], v206 offset:12416
	v_mfma_f32_32x32x16_bf16 v[66:81], v[226:229], v[106:109], v[66:81]
	v_mfma_f32_32x32x16_bf16 v[66:81], v[230:233], v[102:105], v[66:81]
	v_mfma_f32_32x32x16_bf16 v[66:81], v[234:237], v[98:101], v[66:81]
	ds_read_b128 v[210:213], v203 offset:12544
	ds_read_b128 v[214:217], v204 offset:12544
	ds_read_b128 v[222:225], v205 offset:12544
	ds_read_b128 v[204:207], v206 offset:12544
	s_waitcnt lgkmcnt(0)
	v_mfma_f32_32x32x16_bf16 v[66:81], v[130:133], v[94:97], v[66:81]
	v_add_u32_e32 v203, v202, v196
	v_add_u32_e32 v202, v202, v197
	v_mfma_f32_32x32x16_bf16 v[66:81], v[134:137], v[90:93], v[66:81]
	v_mfma_f32_32x32x16_bf16 v[66:81], v[138:141], v[86:89], v[66:81]
	v_mfma_f32_32x32x16_bf16 v[66:81], v[142:145], v[82:85], v[66:81]
	ds_read_b128 v[138:141], v203 offset:24576
	ds_read_b128 v[130:133], v203 offset:28672
	ds_read_b128 v[142:145], v202 offset:24576
	ds_read_b128 v[134:137], v202 offset:28672
	v_mfma_f32_32x32x16_bf16 v[66:81], v[210:213], v[118:121], v[66:81]
	v_mfma_f32_32x32x16_bf16 v[66:81], v[214:217], v[126:129], v[66:81]
	v_mfma_f32_32x32x16_bf16 v[66:81], v[222:225], v[114:117], v[66:81]
	v_mfma_f32_32x32x16_bf16 v[66:81], v[204:207], v[122:125], v[66:81]
	s_setprio 0
	s_nop 10
	v_mul_f32_e32 v212, 0x3dd53b94, v66
	v_mul_f32_e32 v211, 0x3dd53b94, v67
	v_mul_f32_e32 v210, 0x3dd53b94, v68
	v_mul_f32_e32 v208, 0x3dd53b94, v69
	v_mul_f32_e32 v204, 0x3dd53b94, v73
	v_mul_f32_e32 v73, 0x3dd53b94, v74
	v_max3_f32 v74, v212, s3, v211
	v_mul_f32_e32 v207, 0x3dd53b94, v70
	v_mul_f32_e32 v206, 0x3dd53b94, v71
	v_max3_f32 v74, v74, v210, v208
	v_mul_f32_e32 v205, 0x3dd53b94, v72
	v_max3_f32 v74, v74, v207, v206
	v_mul_f32_e32 v72, 0x3dd53b94, v75
	v_max3_f32 v74, v74, v205, v204
	v_mul_f32_e32 v71, 0x3dd53b94, v76
	v_mul_f32_e32 v70, 0x3dd53b94, v77
	v_max3_f32 v74, v74, v73, v72
	v_mul_f32_e32 v69, 0x3dd53b94, v78
	v_mul_f32_e32 v68, 0x3dd53b94, v79
	v_max3_f32 v74, v74, v71, v70
	v_mul_f32_e32 v67, 0x3dd53b94, v80
	v_mul_f32_e32 v66, 0x3dd53b94, v81
	v_max3_f32 v74, v74, v69, v68
	v_max3_f32 v74, v74, v67, v66
	v_mov_b32_e32 v75, v74
	s_nop 1
	v_permlane32_swap_b32_e32 v74, v75
	v_max_f32_e32 v74, v74, v75
	v_cmp_le_f32_e32 vcc, v74, v209
	s_cmp_eq_u64 vcc, exec
	s_cbranch_scc1 .LBB0_866
	v_max_f32_e32 v74, v74, v74
	v_max_f32_e32 v75, v198, v198
	v_max_f32_e32 v75, v75, v74
	v_sub_f32_e32 v74, v198, v75
	v_exp_f32_e32 v74, v74
	v_mov_b32_e32 v198, v75
	v_mul_f32_e32 v201, v201, v74
	v_pk_mul_f32 v[64:65], v[64:65], v[74:75] op_sel_hi:[1,0]
	v_pk_mul_f32 v[62:63], v[62:63], v[74:75] op_sel_hi:[1,0]
	v_pk_mul_f32 v[60:61], v[60:61], v[74:75] op_sel_hi:[1,0]
	v_pk_mul_f32 v[58:59], v[58:59], v[74:75] op_sel_hi:[1,0]
	v_pk_mul_f32 v[56:57], v[56:57], v[74:75] op_sel_hi:[1,0]
	v_pk_mul_f32 v[54:55], v[54:55], v[74:75] op_sel_hi:[1,0]
	v_pk_mul_f32 v[52:53], v[52:53], v[74:75] op_sel_hi:[1,0]
	v_pk_mul_f32 v[50:51], v[50:51], v[74:75] op_sel_hi:[1,0]
	v_pk_mul_f32 v[48:49], v[48:49], v[74:75] op_sel_hi:[1,0]
	v_pk_mul_f32 v[46:47], v[46:47], v[74:75] op_sel_hi:[1,0]
	v_pk_mul_f32 v[44:45], v[44:45], v[74:75] op_sel_hi:[1,0]
	v_pk_mul_f32 v[42:43], v[42:43], v[74:75] op_sel_hi:[1,0]
	v_pk_mul_f32 v[40:41], v[40:41], v[74:75] op_sel_hi:[1,0]
	v_pk_mul_f32 v[38:39], v[38:39], v[74:75] op_sel_hi:[1,0]
	v_pk_mul_f32 v[36:37], v[36:37], v[74:75] op_sel_hi:[1,0]
	v_pk_mul_f32 v[34:35], v[34:35], v[74:75] op_sel_hi:[1,0]
	v_pk_mul_f32 v[32:33], v[32:33], v[74:75] op_sel_hi:[1,0]
	v_pk_mul_f32 v[30:31], v[30:31], v[74:75] op_sel_hi:[1,0]
	v_pk_mul_f32 v[28:29], v[28:29], v[74:75] op_sel_hi:[1,0]
	v_pk_mul_f32 v[26:27], v[26:27], v[74:75] op_sel_hi:[1,0]
	v_pk_mul_f32 v[24:25], v[24:25], v[74:75] op_sel_hi:[1,0]
	v_pk_mul_f32 v[22:23], v[22:23], v[74:75] op_sel_hi:[1,0]
	v_pk_mul_f32 v[20:21], v[20:21], v[74:75] op_sel_hi:[1,0]
	v_pk_mul_f32 v[18:19], v[18:19], v[74:75] op_sel_hi:[1,0]
	v_pk_mul_f32 v[16:17], v[16:17], v[74:75] op_sel_hi:[1,0]
	v_pk_mul_f32 v[14:15], v[14:15], v[74:75] op_sel_hi:[1,0]
	v_pk_mul_f32 v[12:13], v[12:13], v[74:75] op_sel_hi:[1,0]
	v_pk_mul_f32 v[10:11], v[10:11], v[74:75] op_sel_hi:[1,0]
	v_pk_mul_f32 v[8:9], v[8:9], v[74:75] op_sel_hi:[1,0]
	v_pk_mul_f32 v[6:7], v[6:7], v[74:75] op_sel_hi:[1,0]
	v_pk_mul_f32 v[4:5], v[4:5], v[74:75] op_sel_hi:[1,0]
	v_pk_mul_f32 v[2:3], v[2:3], v[74:75] op_sel_hi:[1,0]
	s_branch .LBB0_866
